# prep x stream 4 chunks in flight; both LayerNorm phases hand-written (g/b in registers, next row prefetched, DPP reductions)
# speedup vs baseline: 1.1302x; 1.0077x over previous
; DI void cvt_stream(const float* __restrict__ src, u16* __restrict__ dst, size_t n, size_t gtid, size_t gn) {
;   size_t n8 = n / 8;
;   for (size_t i = gtid; i < n8; i += gn) {
;     f32x4 a = *reinterpret_cast<const f32x4*>(src + i * 8);
;     f32x4 b = *reinterpret_cast<const f32x4*>(src + i * 8 + 4);
;     u32x4 r; r[0] = pk_bf16(a[0], a[1]); r[1] = pk_bf16(a[2], a[3]); r[2] = pk_bf16(b[0], b[1]); r[3] = pk_bf16(b[2], b[3]);
;     *reinterpret_cast<u32x4*>(dst + i * 8) = r;
;   }
; }
; DI void phase_prep(const Params& p, char* smem) {
;     ...
;   cvt_stream(p.x, (u16*)(ws + OFF_XB), (size_t)T_ * 1024, gtid, gn);
.LBB0_7:
	s_mov_b32 s12, 8
.Lprep_x_loop:
	v_lshl_add_u64 v[22:23], v[4:5], 0, s[8:9]
	v_lshl_add_u64 v[24:25], v[22:23], 0, s[8:9]
	v_lshl_add_u64 v[26:27], v[24:25], 0, s[8:9]
	global_load_dwordx4 v[28:31], v[4:5], off offset:-16
	global_load_dwordx4 v[32:35], v[4:5], off
	global_load_dwordx4 v[36:39], v[22:23], off offset:-16
	global_load_dwordx4 v[40:43], v[22:23], off
	global_load_dwordx4 v[44:47], v[24:25], off offset:-16
	global_load_dwordx4 v[48:51], v[24:25], off
	global_load_dwordx4 v[52:55], v[26:27], off offset:-16
	global_load_dwordx4 v[56:59], v[26:27], off
	v_lshl_add_u64 v[4:5], v[26:27], 0, s[8:9]
	s_waitcnt vmcnt(6)
	v_cvt_pk_bf16_f32 v10, v28, v29
	v_cvt_pk_bf16_f32 v11, v30, v31
	v_cvt_pk_bf16_f32 v12, v32, v33
	v_cvt_pk_bf16_f32 v13, v34, v35
	global_store_dwordx4 v[6:7], v[10:13], off
	v_lshl_add_u64 v[6:7], v[6:7], 0, s[10:11]
	s_nop 0
	s_waitcnt vmcnt(5)
	v_cvt_pk_bf16_f32 v10, v36, v37
	v_cvt_pk_bf16_f32 v11, v38, v39
	v_cvt_pk_bf16_f32 v12, v40, v41
	v_cvt_pk_bf16_f32 v13, v42, v43
	global_store_dwordx4 v[6:7], v[10:13], off
	v_lshl_add_u64 v[6:7], v[6:7], 0, s[10:11]
	s_nop 0
	s_waitcnt vmcnt(4)
	v_cvt_pk_bf16_f32 v10, v44, v45
	v_cvt_pk_bf16_f32 v11, v46, v47
	v_cvt_pk_bf16_f32 v12, v48, v49
	v_cvt_pk_bf16_f32 v13, v50, v51
	global_store_dwordx4 v[6:7], v[10:13], off
	v_lshl_add_u64 v[6:7], v[6:7], 0, s[10:11]
	s_nop 0
	s_waitcnt vmcnt(3)
	v_cvt_pk_bf16_f32 v10, v52, v53
	v_cvt_pk_bf16_f32 v11, v54, v55
	v_cvt_pk_bf16_f32 v12, v56, v57
	v_cvt_pk_bf16_f32 v13, v58, v59
	global_store_dwordx4 v[6:7], v[10:13], off
	v_lshl_add_u64 v[6:7], v[6:7], 0, s[10:11]
	s_nop 0
	s_add_i32 s12, s12, -1
	s_cmp_lg_u32 s12, 0
	s_cbranch_scc1 .Lprep_x_loop

; DI void phase_ln(const Params& p, float* h, u16* hb, const float* g, const float* bta) {
;   const int lane = threadIdx.x & 63;
;   const int xg = blockIdx.x & 7, xw = (blockIdx.x >> 3) * 8 + (threadIdx.x >> 6), xnw = (gridDim.x >> 3) * 8;
;   for (int lrw = xw; lrw < 4096; lrw += xnw) {
;     const int row = (xg + 8 * (lrw >> 8)) * 256 + (lrw & 255);
;     float* r = h + (size_t)row * 1024;
;     f32x4 v[4]; float s = 0.f;
; #pragma unroll
;     for (int c = 0; c < 4; ++c) { v[c] = *reinterpret_cast<const f32x4*>(r + c * 256 + lane * 4); s += v[c][0] + v[c][1] + v[c][2] + v[c][3]; }
;     const float mean = wave_sum(s) * (1.f / 1024.f);
;     float q = 0.f;
; #pragma unroll
;     for (int c = 0; c < 4; ++c)
; #pragma unroll
;       for (int k = 0; k < 4; ++k) { float d = v[c][k] - mean; q += d * d; }
;     const float rstd = rsqrtf(wave_sum(q) * (1.f / 1024.f) + 1e-5f);
; #pragma unroll
;     for (int c = 0; c < 4; ++c) {
;       f32x4 gg = *reinterpret_cast<const f32x4*>(g + c * 256 + lane * 4);
;       f32x4 bb = *reinterpret_cast<const f32x4*>(bta + c * 256 + lane * 4);
;       f32x4 o;
; #pragma unroll
;       for (int k = 0; k < 4; ++k) o[k] = (v[c][k] - mean) * rstd * gg[k] + bb[k];
;       *reinterpret_cast<f32x4*>(r + c * 256 + lane * 4) = o;
;       st4bf(hb + (size_t)row * 1024 + c * 256 + lane * 4, o[0], o[1], o[2], o[3]);
;     }
;   }
; }
.LBB0_621:
	s_or_b64 exec, exec, s[0:1]
	s_add_u32 s60, s96, 0x12800000
	s_addc_u32 s61, s97, 0
	s_and_b32 s79, s2, -8
	v_add_u32_e32 v147, s79, v167
	s_and_b32 s3, s78, -8
	s_movk_i32 s0, 0x1000
	s_waitcnt lgkmcnt(0)
	s_barrier
	v_cmp_gt_i32_e64 s[4:5], s0, v147
	s_mov_b64 s[0:1], exec
	s_nop 0
	v_writelane_b32 v255, s4, 47
	s_nop 1
	v_writelane_b32 v255, s5, 48
	s_and_b64 s[4:5], s[0:1], s[4:5]
	s_mov_b64 exec, s[4:5]
	s_cbranch_execz .LBB0_624
	s_and_b32 s4, s2, -8
	v_add_u32_e32 v0, s4, v167
	v_mov_b32_e32 v1, s33
	v_lshl_add_u32 v0, v1, 8, v0
	v_lshlrev_b32_e32 v6, 4, v177
	v_lshlrev_b32_e32 v1, 3, v177
	v_lshl_add_u32 v4, v0, 12, v6
	v_lshl_add_u32 v5, v0, 11, v1
	global_load_dwordx4 v[100:103], v6, s[52:53]
	global_load_dwordx4 v[104:107], v6, s[52:53] offset:1024
	global_load_dwordx4 v[108:111], v6, s[52:53] offset:2048
	global_load_dwordx4 v[112:115], v6, s[52:53] offset:3072
	global_load_dwordx4 v[116:119], v6, s[54:55]
	global_load_dwordx4 v[120:123], v6, s[54:55] offset:1024
	global_load_dwordx4 v[124:127], v6, s[54:55] offset:2048
	global_load_dwordx4 v[128:131], v6, s[54:55] offset:3072
	global_load_dwordx4 v[16:19], v4, s[82:83]
	global_load_dwordx4 v[20:23], v4, s[82:83] offset:1024
	global_load_dwordx4 v[24:27], v4, s[82:83] offset:2048
	global_load_dwordx4 v[28:31], v4, s[82:83] offset:3072
	v_mov_b32_e32 v7, 0x3727c5ac
	s_mov_b32 s5, 16
	s_waitcnt vmcnt(0)
.Lln1_loop:
	s_cmp_gt_u32 s5, 1
	s_cselect_b32 s4, 0x800000, 0
	v_add_u32_e32 v8, s4, v4
	global_load_dwordx4 v[32:35], v8, s[82:83]
	global_load_dwordx4 v[36:39], v8, s[82:83] offset:1024
	global_load_dwordx4 v[40:43], v8, s[82:83] offset:2048
	global_load_dwordx4 v[44:47], v8, s[82:83] offset:3072
	s_waitcnt vmcnt(12)
	v_pk_add_f32 v[64:65], v[16:17], v[18:19]
	v_pk_add_f32 v[66:67], v[20:21], v[22:23]
	v_pk_add_f32 v[68:69], v[24:25], v[26:27]
	v_pk_add_f32 v[70:71], v[28:29], v[30:31]
	v_pk_add_f32 v[64:65], v[64:65], v[66:67]
	v_pk_add_f32 v[68:69], v[68:69], v[70:71]
	s_nop 0
	v_pk_add_f32 v[64:65], v[64:65], v[68:69]
	s_nop 0
	v_add_f32_e32 v64, v64, v65
	s_nop 1
	v_add_f32_dpp v65, v64, v64 quad_perm:[1,0,3,2] row_mask:0xf bank_mask:0xf
	s_nop 1
	v_add_f32_dpp v64, v65, v65 quad_perm:[2,3,0,1] row_mask:0xf bank_mask:0xf
	s_nop 1
	v_add_f32_dpp v65, v64, v64 row_half_mirror row_mask:0xf bank_mask:0xf
	s_nop 1
	v_add_f32_dpp v64, v65, v65 row_mirror row_mask:0xf bank_mask:0xf
	s_nop 1
	v_readlane_b32 s6, v64, 0
	v_readlane_b32 s7, v64, 16
	v_readlane_b32 s8, v64, 32
	v_readlane_b32 s9, v64, 48
	s_nop 1
	v_mov_b32_e32 v65, s6
	v_add_f32_e32 v65, s7, v65
	v_add_f32_e32 v65, s8, v65
	v_add_f32_e32 v65, s9, v65
	v_mul_f32_e32 v66, 0x3a800000, v65
	v_mov_b32_e32 v67, v66
	v_pk_add_f32 v[48:49], v[16:17], v[66:67] neg_lo:[0,1] neg_hi:[0,1]
	v_pk_add_f32 v[50:51], v[18:19], v[66:67] neg_lo:[0,1] neg_hi:[0,1]
	v_pk_add_f32 v[52:53], v[20:21], v[66:67] neg_lo:[0,1] neg_hi:[0,1]
	v_pk_add_f32 v[54:55], v[22:23], v[66:67] neg_lo:[0,1] neg_hi:[0,1]
	v_pk_add_f32 v[56:57], v[24:25], v[66:67] neg_lo:[0,1] neg_hi:[0,1]
	v_pk_add_f32 v[58:59], v[26:27], v[66:67] neg_lo:[0,1] neg_hi:[0,1]
	v_pk_add_f32 v[60:61], v[28:29], v[66:67] neg_lo:[0,1] neg_hi:[0,1]
	v_pk_add_f32 v[62:63], v[30:31], v[66:67] neg_lo:[0,1] neg_hi:[0,1]
	v_pk_mul_f32 v[64:65], v[48:49], v[48:49]
	v_pk_mul_f32 v[68:69], v[50:51], v[50:51]
	v_pk_fma_f32 v[64:65], v[52:53], v[52:53], v[64:65]
	v_pk_fma_f32 v[68:69], v[54:55], v[54:55], v[68:69]
	v_pk_fma_f32 v[64:65], v[56:57], v[56:57], v[64:65]
	v_pk_fma_f32 v[68:69], v[58:59], v[58:59], v[68:69]
	v_pk_fma_f32 v[64:65], v[60:61], v[60:61], v[64:65]
	v_pk_fma_f32 v[68:69], v[62:63], v[62:63], v[68:69]
	v_pk_add_f32 v[64:65], v[64:65], v[68:69]
	s_nop 0
	v_add_f32_e32 v64, v64, v65
	s_nop 1
	v_add_f32_dpp v65, v64, v64 quad_perm:[1,0,3,2] row_mask:0xf bank_mask:0xf
	s_nop 1
	v_add_f32_dpp v64, v65, v65 quad_perm:[2,3,0,1] row_mask:0xf bank_mask:0xf
	s_nop 1
	v_add_f32_dpp v65, v64, v64 row_half_mirror row_mask:0xf bank_mask:0xf
	s_nop 1
	v_add_f32_dpp v64, v65, v65 row_mirror row_mask:0xf bank_mask:0xf
	s_nop 1
	v_readlane_b32 s6, v64, 0
	v_readlane_b32 s7, v64, 16
	v_readlane_b32 s8, v64, 32
	v_readlane_b32 s9, v64, 48
	s_nop 1
	v_mov_b32_e32 v65, s6
	v_add_f32_e32 v65, s7, v65
	v_add_f32_e32 v65, s8, v65
	v_add_f32_e32 v65, s9, v65
	v_fmamk_f32 v65, v65, 0x3a800000, v7
	v_rsq_f32_e32 v65, v65
	s_nop 1
	v_mov_b32_e32 v64, v65
	s_nop 0
	v_pk_mul_f32 v[48:49], v[48:49], v[64:65]
	v_pk_mul_f32 v[50:51], v[50:51], v[64:65]
	v_pk_mul_f32 v[52:53], v[52:53], v[64:65]
	v_pk_mul_f32 v[54:55], v[54:55], v[64:65]
	v_pk_mul_f32 v[56:57], v[56:57], v[64:65]
	v_pk_mul_f32 v[58:59], v[58:59], v[64:65]
	v_pk_mul_f32 v[60:61], v[60:61], v[64:65]
	v_pk_mul_f32 v[62:63], v[62:63], v[64:65]
	v_pk_fma_f32 v[48:49], v[48:49], v[100:101], v[116:117]
	v_pk_fma_f32 v[50:51], v[50:51], v[102:103], v[118:119]
	v_pk_fma_f32 v[52:53], v[52:53], v[104:105], v[120:121]
	v_pk_fma_f32 v[54:55], v[54:55], v[106:107], v[122:123]
	v_pk_fma_f32 v[56:57], v[56:57], v[108:109], v[124:125]
	v_pk_fma_f32 v[58:59], v[58:59], v[110:111], v[126:127]
	v_pk_fma_f32 v[60:61], v[60:61], v[112:113], v[128:129]
	v_pk_fma_f32 v[62:63], v[62:63], v[114:115], v[130:131]
	global_store_dwordx4 v4, v[48:51], s[82:83]
	global_store_dwordx4 v4, v[52:55], s[82:83] offset:1024
	global_store_dwordx4 v4, v[56:59], s[82:83] offset:2048
	global_store_dwordx4 v4, v[60:63], s[82:83] offset:3072
	v_cvt_pk_bf16_f32 v72, v48, v49
	v_cvt_pk_bf16_f32 v73, v50, v51
	v_cvt_pk_bf16_f32 v74, v52, v53
	v_cvt_pk_bf16_f32 v75, v54, v55
	v_cvt_pk_bf16_f32 v76, v56, v57
	v_cvt_pk_bf16_f32 v77, v58, v59
	v_cvt_pk_bf16_f32 v78, v60, v61
	v_cvt_pk_bf16_f32 v79, v62, v63
	global_store_dwordx2 v5, v[72:73], s[60:61]
	global_store_dwordx2 v5, v[74:75], s[60:61] offset:512
	global_store_dwordx2 v5, v[76:77], s[60:61] offset:1024
	global_store_dwordx2 v5, v[78:79], s[60:61] offset:1536
	v_add_u32_e32 v4, 0x800000, v4
	v_add_u32_e32 v5, 0x400000, v5
	s_add_i32 s5, s5, -1
	s_cmp_gt_u32 s5, 1
	s_cselect_b32 s4, 0x800000, 0
	v_add_u32_e32 v8, s4, v4
	global_load_dwordx4 v[16:19], v8, s[82:83]
	global_load_dwordx4 v[20:23], v8, s[82:83] offset:1024
	global_load_dwordx4 v[24:27], v8, s[82:83] offset:2048
	global_load_dwordx4 v[28:31], v8, s[82:83] offset:3072
	s_waitcnt vmcnt(12)
; DI void phase_ln(const Params& p, float* h, u16* hb, const float* g, const float* bta) {
;   const int lane = threadIdx.x & 63;
;   const int xg = blockIdx.x & 7, xw = (blockIdx.x >> 3) * 8 + (threadIdx.x >> 6), xnw = (gridDim.x >> 3) * 8;
;   for (int lrw = xw; lrw < 4096; lrw += xnw) {
;     const int row = (xg + 8 * (lrw >> 8)) * 256 + (lrw & 255);
;     float* r = h + (size_t)row * 1024;
;     f32x4 v[4]; float s = 0.f;
; #pragma unroll
;     for (int c = 0; c < 4; ++c) { v[c] = *reinterpret_cast<const f32x4*>(r + c * 256 + lane * 4); s += v[c][0] + v[c][1] + v[c][2] + v[c][3]; }
;     const float mean = wave_sum(s) * (1.f / 1024.f);
;     float q = 0.f;
; #pragma unroll
;     for (int c = 0; c < 4; ++c)
; #pragma unroll
;       for (int k = 0; k < 4; ++k) { float d = v[c][k] - mean; q += d * d; }
;     const float rstd = rsqrtf(wave_sum(q) * (1.f / 1024.f) + 1e-5f);
; #pragma unroll
;     for (int c = 0; c < 4; ++c) {
;       f32x4 gg = *reinterpret_cast<const f32x4*>(g + c * 256 + lane * 4);
;       f32x4 bb = *reinterpret_cast<const f32x4*>(bta + c * 256 + lane * 4);
;       f32x4 o;
; #pragma unroll
;       for (int k = 0; k < 4; ++k) o[k] = (v[c][k] - mean) * rstd * gg[k] + bb[k];
;       *reinterpret_cast<f32x4*>(r + c * 256 + lane * 4) = o;
;       st4bf(hb + (size_t)row * 1024 + c * 256 + lane * 4, o[0], o[1], o[2], o[3]);
;     }
;   }
; }
	v_pk_add_f32 v[64:65], v[32:33], v[34:35]
	v_pk_add_f32 v[66:67], v[36:37], v[38:39]
	v_pk_add_f32 v[68:69], v[40:41], v[42:43]
	v_pk_add_f32 v[70:71], v[44:45], v[46:47]
	v_pk_add_f32 v[64:65], v[64:65], v[66:67]
	v_pk_add_f32 v[68:69], v[68:69], v[70:71]
	s_nop 0
	v_pk_add_f32 v[64:65], v[64:65], v[68:69]
	s_nop 0
	v_add_f32_e32 v64, v64, v65
	s_nop 1
	v_add_f32_dpp v65, v64, v64 quad_perm:[1,0,3,2] row_mask:0xf bank_mask:0xf
	s_nop 1
	v_add_f32_dpp v64, v65, v65 quad_perm:[2,3,0,1] row_mask:0xf bank_mask:0xf
	s_nop 1
	v_add_f32_dpp v65, v64, v64 row_half_mirror row_mask:0xf bank_mask:0xf
	s_nop 1
	v_add_f32_dpp v64, v65, v65 row_mirror row_mask:0xf bank_mask:0xf
	s_nop 1
	v_readlane_b32 s6, v64, 0
	v_readlane_b32 s7, v64, 16
	v_readlane_b32 s8, v64, 32
	v_readlane_b32 s9, v64, 48
	s_nop 1
	v_mov_b32_e32 v65, s6
	v_add_f32_e32 v65, s7, v65
	v_add_f32_e32 v65, s8, v65
	v_add_f32_e32 v65, s9, v65
	v_mul_f32_e32 v66, 0x3a800000, v65
	v_mov_b32_e32 v67, v66
	v_pk_add_f32 v[48:49], v[32:33], v[66:67] neg_lo:[0,1] neg_hi:[0,1]
	v_pk_add_f32 v[50:51], v[34:35], v[66:67] neg_lo:[0,1] neg_hi:[0,1]
	v_pk_add_f32 v[52:53], v[36:37], v[66:67] neg_lo:[0,1] neg_hi:[0,1]
	v_pk_add_f32 v[54:55], v[38:39], v[66:67] neg_lo:[0,1] neg_hi:[0,1]
	v_pk_add_f32 v[56:57], v[40:41], v[66:67] neg_lo:[0,1] neg_hi:[0,1]
	v_pk_add_f32 v[58:59], v[42:43], v[66:67] neg_lo:[0,1] neg_hi:[0,1]
	v_pk_add_f32 v[60:61], v[44:45], v[66:67] neg_lo:[0,1] neg_hi:[0,1]
	v_pk_add_f32 v[62:63], v[46:47], v[66:67] neg_lo:[0,1] neg_hi:[0,1]
	v_pk_mul_f32 v[64:65], v[48:49], v[48:49]
	v_pk_mul_f32 v[68:69], v[50:51], v[50:51]
	v_pk_fma_f32 v[64:65], v[52:53], v[52:53], v[64:65]
	v_pk_fma_f32 v[68:69], v[54:55], v[54:55], v[68:69]
	v_pk_fma_f32 v[64:65], v[56:57], v[56:57], v[64:65]
	v_pk_fma_f32 v[68:69], v[58:59], v[58:59], v[68:69]
	v_pk_fma_f32 v[64:65], v[60:61], v[60:61], v[64:65]
	v_pk_fma_f32 v[68:69], v[62:63], v[62:63], v[68:69]
	v_pk_add_f32 v[64:65], v[64:65], v[68:69]
	s_nop 0
	v_add_f32_e32 v64, v64, v65
	s_nop 1
	v_add_f32_dpp v65, v64, v64 quad_perm:[1,0,3,2] row_mask:0xf bank_mask:0xf
	s_nop 1
	v_add_f32_dpp v64, v65, v65 quad_perm:[2,3,0,1] row_mask:0xf bank_mask:0xf
	s_nop 1
	v_add_f32_dpp v65, v64, v64 row_half_mirror row_mask:0xf bank_mask:0xf
	s_nop 1
	v_add_f32_dpp v64, v65, v65 row_mirror row_mask:0xf bank_mask:0xf
	s_nop 1
	v_readlane_b32 s6, v64, 0
	v_readlane_b32 s7, v64, 16
	v_readlane_b32 s8, v64, 32
	v_readlane_b32 s9, v64, 48
	s_nop 1
	v_mov_b32_e32 v65, s6
	v_add_f32_e32 v65, s7, v65
	v_add_f32_e32 v65, s8, v65
	v_add_f32_e32 v65, s9, v65
	v_fmamk_f32 v65, v65, 0x3a800000, v7
	v_rsq_f32_e32 v65, v65
	s_nop 1
	v_mov_b32_e32 v64, v65
	s_nop 0
	v_pk_mul_f32 v[48:49], v[48:49], v[64:65]
	v_pk_mul_f32 v[50:51], v[50:51], v[64:65]
	v_pk_mul_f32 v[52:53], v[52:53], v[64:65]
	v_pk_mul_f32 v[54:55], v[54:55], v[64:65]
	v_pk_mul_f32 v[56:57], v[56:57], v[64:65]
	v_pk_mul_f32 v[58:59], v[58:59], v[64:65]
	v_pk_mul_f32 v[60:61], v[60:61], v[64:65]
	v_pk_mul_f32 v[62:63], v[62:63], v[64:65]
	v_pk_fma_f32 v[48:49], v[48:49], v[100:101], v[116:117]
	v_pk_fma_f32 v[50:51], v[50:51], v[102:103], v[118:119]
	v_pk_fma_f32 v[52:53], v[52:53], v[104:105], v[120:121]
	v_pk_fma_f32 v[54:55], v[54:55], v[106:107], v[122:123]
	v_pk_fma_f32 v[56:57], v[56:57], v[108:109], v[124:125]
	v_pk_fma_f32 v[58:59], v[58:59], v[110:111], v[126:127]
	v_pk_fma_f32 v[60:61], v[60:61], v[112:113], v[128:129]
	v_pk_fma_f32 v[62:63], v[62:63], v[114:115], v[130:131]
	global_store_dwordx4 v4, v[48:51], s[82:83]
	global_store_dwordx4 v4, v[52:55], s[82:83] offset:1024
	global_store_dwordx4 v4, v[56:59], s[82:83] offset:2048
	global_store_dwordx4 v4, v[60:63], s[82:83] offset:3072
	v_cvt_pk_bf16_f32 v72, v48, v49
	v_cvt_pk_bf16_f32 v73, v50, v51
	v_cvt_pk_bf16_f32 v74, v52, v53
	v_cvt_pk_bf16_f32 v75, v54, v55
	v_cvt_pk_bf16_f32 v76, v56, v57
	v_cvt_pk_bf16_f32 v77, v58, v59
	v_cvt_pk_bf16_f32 v78, v60, v61
	v_cvt_pk_bf16_f32 v79, v62, v63
	global_store_dwordx2 v5, v[72:73], s[60:61]
	global_store_dwordx2 v5, v[74:75], s[60:61] offset:512
	global_store_dwordx2 v5, v[76:77], s[60:61] offset:1024
	global_store_dwordx2 v5, v[78:79], s[60:61] offset:1536
	v_add_u32_e32 v4, 0x800000, v4
	v_add_u32_e32 v5, 0x400000, v5
	s_add_i32 s5, s5, -1
	s_cmp_lg_u32 s5, 0
	s_cbranch_scc1 .Lln1_loop

; DI void phase_ln(const Params& p, float* h, u16* hb, const float* g, const float* bta) {
;   const int lane = threadIdx.x & 63;
;   const int xg = blockIdx.x & 7, xw = (blockIdx.x >> 3) * 8 + (threadIdx.x >> 6), xnw = (gridDim.x >> 3) * 8;
;   for (int lrw = xw; lrw < 4096; lrw += xnw) {
;     const int row = (xg + 8 * (lrw >> 8)) * 256 + (lrw & 255);
;     float* r = h + (size_t)row * 1024;
;     f32x4 v[4]; float s = 0.f;
; #pragma unroll
;     for (int c = 0; c < 4; ++c) { v[c] = *reinterpret_cast<const f32x4*>(r + c * 256 + lane * 4); s += v[c][0] + v[c][1] + v[c][2] + v[c][3]; }
;     const float mean = wave_sum(s) * (1.f / 1024.f);
;     float q = 0.f;
; #pragma unroll
;     for (int c = 0; c < 4; ++c)
; #pragma unroll
;       for (int k = 0; k < 4; ++k) { float d = v[c][k] - mean; q += d * d; }
;     const float rstd = rsqrtf(wave_sum(q) * (1.f / 1024.f) + 1e-5f);
; #pragma unroll
;     for (int c = 0; c < 4; ++c) {
;       f32x4 gg = *reinterpret_cast<const f32x4*>(g + c * 256 + lane * 4);
;       f32x4 bb = *reinterpret_cast<const f32x4*>(bta + c * 256 + lane * 4);
;       f32x4 o;
; #pragma unroll
;       for (int k = 0; k < 4; ++k) o[k] = (v[c][k] - mean) * rstd * gg[k] + bb[k];
;       *reinterpret_cast<f32x4*>(r + c * 256 + lane * 4) = o;
;       st4bf(hb + (size_t)row * 1024 + c * 256 + lane * 4, o[0], o[1], o[2], o[3]);
;     }
;   }
; }
.LBB0_849:
	s_or_b64 exec, exec, s[10:11]
	s_waitcnt lgkmcnt(0)
	s_barrier
	s_mov_b64 s[10:11], exec
	v_readlane_b32 s0, v255, 47
	v_readlane_b32 s1, v255, 48
	s_and_b64 s[0:1], s[10:11], s[0:1]
	s_mov_b64 exec, s[0:1]
	s_cbranch_execz .LBB0_852
	s_and_b32 s4, s2, -8
	v_add_u32_e32 v0, s4, v167
	v_mov_b32_e32 v1, s33
	v_lshl_add_u32 v0, v1, 8, v0
	v_lshlrev_b32_e32 v6, 4, v177
	v_lshlrev_b32_e32 v1, 3, v177
	v_lshl_add_u32 v4, v0, 12, v6
	v_lshl_add_u32 v5, v0, 11, v1
	global_load_dwordx4 v[100:103], v6, s[64:65]
	global_load_dwordx4 v[104:107], v6, s[64:65] offset:1024
	global_load_dwordx4 v[108:111], v6, s[64:65] offset:2048
	global_load_dwordx4 v[112:115], v6, s[64:65] offset:3072
	global_load_dwordx4 v[116:119], v6, s[66:67]
	global_load_dwordx4 v[120:123], v6, s[66:67] offset:1024
	global_load_dwordx4 v[124:127], v6, s[66:67] offset:2048
	global_load_dwordx4 v[128:131], v6, s[66:67] offset:3072
	global_load_dwordx4 v[16:19], v4, s[82:83]
	global_load_dwordx4 v[20:23], v4, s[82:83] offset:1024
	global_load_dwordx4 v[24:27], v4, s[82:83] offset:2048
	global_load_dwordx4 v[28:31], v4, s[82:83] offset:3072
	v_mov_b32_e32 v7, 0x3727c5ac
	s_mov_b32 s5, 16
	s_waitcnt vmcnt(0)
